# attention K/V tile loads: SGPR tile base + per-item 32-bit VGPR offsets instead of per-tile 64-bit VALU address math
# speedup vs baseline: 1.0202x; 1.0013x over previous
; __device__ __forceinline__ void lds_barrier() { asm volatile("s_waitcnt lgkmcnt(0)\n\ts_barrier" ::: "memory"); }
; __device__ __forceinline__ void attn_item(const Params& p, unsigned char* smem, int b, int h, int qb, float lam) {
;     ...
;   u16* AQ = (u16*)(p.ws + OFF_AQ); const u16* AK = (const u16*)(p.ws + OFF_AK); const u16* AVT = (const u16*)(p.ws + OFF_AVT);
;   u16* sK = (u16*)smem;
;   float* sO = (float*)smem;
;   const int t0 = qb * 64; const int ntiles = qb + 2;
;   const size_t qrow = (size_t)(b * LTOK + NMETA + t0 + r0 + l31);
;   bf16x8 qf[4];
; #pragma unroll
;   for (int s = 0; s < 4; ++s) qf[s] = *(const bf16x8*)(AQ + qrow * 1024 + h * 128 + map * 64 + s * 16 + hf * 8);
;   f32x16 oacc[4];
; #pragma unroll
;   for (int d = 0; d < 4; ++d)
; #pragma unroll
;     for (int r = 0; r < 16; ++r) oacc[d][r] = 0.f;
;   float m_run = -1e30f, l_run = 0.f;
;   const int qpos = NMETA + t0 + r0 + l31;
;   const u16* kbase = AK + ((size_t)b * LPAD) * 1024 + h * 128;
;   const u16* vbase = AVT + ((size_t)(b * 8 + h) * 128) * LPAD;
;   const int kc = tid & 15, kr = tid >> 4;
;   const int vc = tid & 7, vr = tid >> 3;
;   u32x4 ak[4], av[4], bk[4], bv[4];
;   auto gload = [&](u32x4 (&rk)[4], u32x4 (&rv)[4], int kt) {
; #pragma unroll
;     for (int i = 0; i < 4; ++i) {
;       rk[i] = *(const u32x4*)(kbase + (size_t)(kt * 64 + kr + 16 * i) * 1024 + kc * 8);
;       rv[i] = *(const u32x4*)(vbase + (size_t)(vr + 32 * i) * LPAD + kt * 64 + vc * 8);
;     }
;   };
;   auto swrite = [&](const u32x4 (&rk)[4], const u32x4 (&rv)[4], int buf) {
;     ...
;   gload(ak, av, 0); swrite(ak, av, 0); gload(bk, bv, 1);
;   lds_barrier();
.LBB0_329:
	s_or_b64 exec, exec, s[14:15]
	s_waitcnt lgkmcnt(0)
	s_barrier
	ds_read_b32 v0, v179
	s_mov_b64 s[14:15], -1
	s_waitcnt lgkmcnt(0)
	s_barrier
	v_cmp_lt_i32_e32 vcc, s2, v0
	v_readfirstlane_b32 s8, v0
	s_cbranch_vccnz .LBB0_324
	s_and_b32 s16, s8, 1
	s_ashr_i32 s8, s8, 1
	s_sub_i32 s19, 0x7f, s8
	s_lshl_b32 s54, s19, 6
	s_mul_i32 s14, s16, 0x2010
	s_add_i32 s18, s14, s54
	s_add_i32 s18, s18, 16
	s_sub_i32 s53, 0x81, s8
	s_mul_i32 s8, s16, 0x1020000
	s_add_u32 s14, s47, s8
	s_addc_u32 s15, s52, 0
	s_mov_b64 s[84:85], s[14:15]
	s_lshl_b32 s8, s16, 10
	v_mov_b32_e32 v199, v218
	s_or_b32 s8, s8, s46
	s_mulk_i32 s8, 0x4080
	v_ashrrev_i32_e32 v180, 4, v199
	s_add_u32 s16, s41, s8
	v_ashrrev_i32_e32 v181, 31, v180
	s_addc_u32 s17, s42, 0
	s_mov_b64 s[86:87], s[16:17]
	v_lshlrev_b64 v[0:1], 11, v[180:181]
	v_lshlrev_b32_e32 v13, 4, v199
	v_and_b32_e32 v8, 7, v199
	v_ashrrev_i32_e32 v12, 3, v199
	v_lshl_add_u64 v[0:1], s[14:15], 0, v[0:1]
	v_and_b32_e32 v2, 0xf0, v13
	v_mov_b32_e32 v3, v179
	v_mov_b64_e32 v[4:5], s[16:17]
	v_lshl_add_u64 v[0:1], v[0:1], 0, v[2:3]
	v_mad_i64_i32 v[6:7], s[16:17], v12, s20, v[4:5]
	v_lshlrev_b32_e32 v8, 4, v8
	v_mov_b32_e32 v9, v179
	v_lshl_add_u64 v[182:183], v[6:7], 0, v[8:9]
	v_add_co_u32_e32 v6, vcc, s21, v0
	global_load_dwordx4 v[96:99], v[182:183], off
	s_nop 0
	v_addc_co_u32_e32 v7, vcc, 0, v1, vcc
	global_load_dwordx4 v[100:103], v[0:1], off
	global_load_dwordx4 v[104:107], v[6:7], off
	v_add_u32_e32 v6, 32, v12
	v_mad_i64_i32 v[6:7], s[16:17], v6, s20, v[4:5]
	v_lshl_add_u64 v[184:185], v[6:7], 0, v[8:9]
	v_add_co_u32_e32 v6, vcc, s22, v0
	v_add_u32_e32 v10, 64, v12
	s_nop 0
	v_addc_co_u32_e32 v7, vcc, 0, v1, vcc
	v_mad_i64_i32 v[10:11], s[16:17], v10, s20, v[4:5]
	v_lshl_add_u64 v[186:187], v[10:11], 0, v[8:9]
	v_add_co_u32_e32 v10, vcc, s23, v0
	global_load_dwordx4 v[108:111], v[184:185], off
	global_load_dwordx4 v[128:131], v[186:187], off
	v_addc_co_u32_e32 v11, vcc, 0, v1, vcc
	global_load_dwordx4 v[132:135], v[6:7], off
	global_load_dwordx4 v[136:139], v[10:11], off
	v_add_u32_e32 v6, 0x60, v12
	v_mad_i64_i32 v[4:5], s[16:17], v6, s20, v[4:5]
	v_lshl_add_u64 v[190:191], v[4:5], 0, v[8:9]
	v_lshrrev_b32_e32 v4, 1, v199
	v_and_b32_e32 v181, 31, v199
	v_and_b32_e32 v200, 32, v4
	v_add3_u32 v178, v181, s18, v200
	v_ashrrev_i32_e32 v6, 1, v199
	v_lshlrev_b64 v[4:5], 11, v[178:179]
	v_and_b32_e32 v188, 0xffffffc0, v6
	v_bfe_u32 v8, v199, 5, 1
	v_lshl_add_u64 v[4:5], s[12:13], 0, v[4:5]
	v_ashrrev_i32_e32 v189, 31, v188
	v_lshl_add_u64 v[4:5], v[188:189], 1, v[4:5]
	v_lshlrev_b32_e32 v178, 4, v8
	v_lshl_add_u64 v[4:5], v[4:5], 0, v[178:179]
	global_load_dwordx4 v[140:143], v[190:191], off
	global_load_dwordx4 v[112:115], v[4:5], off
	global_load_dwordx4 v[116:119], v[4:5], off offset:32
	global_load_dwordx4 v[120:123], v[4:5], off offset:64
	global_load_dwordx4 v[124:127], v[4:5], off offset:96
	v_add_co_u32_e32 v4, vcc, s26, v0
	global_load_dwordx4 v[144:147], v[182:183], off offset:128
	s_nop 0
	v_addc_co_u32_e32 v5, vcc, 0, v1, vcc
	v_add_co_u32_e32 v6, vcc, s27, v0
	v_mov_b32_e32 v14, v179
	s_nop 0
	v_addc_co_u32_e32 v7, vcc, 0, v1, vcc
	global_load_dwordx4 v[148:151], v[4:5], off
	global_load_dwordx4 v[152:155], v[6:7], off
	global_load_dwordx4 v[156:159], v[184:185], off offset:128
	v_add_co_u32_e32 v4, vcc, s28, v0
	global_load_dwordx4 v[160:163], v[186:187], off offset:128
	s_nop 0
	v_addc_co_u32_e32 v5, vcc, 0, v1, vcc
	v_add_co_u32_e32 v0, vcc, s29, v0
	v_mov_b32_e32 v15, v179
	s_nop 0
	v_addc_co_u32_e32 v1, vcc, 0, v1, vcc
	global_load_dwordx4 v[164:167], v[4:5], off
	global_load_dwordx4 v[168:171], v[0:1], off
	global_load_dwordx4 v[172:175], v[190:191], off offset:128
	v_or3_b32 v0, s54, v200, v181
	v_mul_lo_u32 v1, v180, s24
	v_add_u32_e32 v189, 16, v0
	v_lshlrev_b32_e32 v0, 3, v199
	v_add3_u32 v201, 16, v1, v2
	v_mul_lo_u32 v1, v12, s25
	v_add_u32_e32 v1, 16, v1
	v_and_b32_e32 v4, 0x60, v13
	v_and_b32_e32 v0, 8, v0
	v_add3_u32 v202, v1, v4, v0
	v_mul_u32_u24_e32 v1, 0x88, v181
	v_lshl_add_u32 v0, v188, 1, 16
	v_lshlrev_b32_e32 v1, 1, v1
	v_cmp_lt_i32_e32 vcc, v198, v195
	v_add_u32_e32 v203, 0x4000, v202
	v_add_u32_e32 v204, 0x5000, v202
	v_add_u32_e32 v205, 0x6800, v202
	v_add_u32_e32 v206, 0x7800, v202
	v_add3_u32 v207, v0, v178, v1
	v_cndmask_b32_e32 v0, v194, v198, vcc
	s_waitcnt vmcnt(18)
	ds_write_b128 v201, v[100:103]
	ds_write2_b64 v203, v[96:97], v[98:99] offset0:128 offset1:130
	s_waitcnt vmcnt(17)
	ds_write_b128 v201, v[104:107] offset:4352
	s_waitcnt vmcnt(16)
	ds_write2_b64 v204, v[108:109], v[110:111] offset0:192 offset1:194
	s_waitcnt vmcnt(14)
	ds_write_b128 v201, v[132:135] offset:8704
	ds_write2_b64 v205, v[128:129], v[130:131] offset1:2
	s_waitcnt vmcnt(13)
	ds_write_b128 v201, v[136:139] offset:13056
	v_lshlrev_b32_e32 v208, 2, v0
	v_mul_u32_u24_e32 v0, 0x48, v181
	v_lshlrev_b32_e32 v0, 1, v0
	v_lshlrev_b32_e32 v248, 11, v180
	v_add_u32_e32 v248, v248, v2
	v_add_u32_e32 v249, 0x8000, v248
	v_add_u32_e32 v250, 0x10000, v248
	v_add_u32_e32 v251, 0x18000, v248
	v_lshrrev_b32_e32 v252, 3, v199
	v_mul_lo_u32 v252, v252, s20
	v_and_b32_e32 v253, 7, v199
	v_lshl_add_u32 v252, v253, 4, v252
	s_lshl_b32 s88, s20, 5
	v_add_u32_e32 v253, s88, v252
	v_add_u32_e32 v254, s88, v253
	v_add_u32_e32 v255, s88, v254
	v_lshl_add_u64 v[192:193], s[14:15], 0, v[2:3]
	v_add3_u32 v209, 16, v0, v178
	v_lshlrev_b32_e32 v210, 2, v8
	v_add_u32_e32 v211, 0xd000, v202
	v_mov_b32_e32 v0, v179
	v_mov_b32_e32 v1, v179
	v_mov_b32_e32 v2, v179
	v_mov_b32_e32 v4, v179
	v_mov_b32_e32 v5, v179
	v_mov_b32_e32 v6, v179
	v_mov_b32_e32 v7, v179
	v_mov_b32_e32 v8, v179
	v_mov_b32_e32 v10, v179
	v_mov_b32_e32 v11, v179
	s_waitcnt vmcnt(12)
	ds_write2_b64 v206, v[140:141], v[142:143] offset0:64 offset1:66
	s_waitcnt lgkmcnt(0)
	s_barrier
	v_mov_b32_e32 v12, v179
	v_mov_b32_e32 v13, v179
	v_mov_b64_e32 v[30:31], v[14:15]
	v_mov_b64_e32 v[46:47], v[14:15]
	v_mov_b64_e32 v[62:63], v[14:15]
	s_mov_b32 s54, 3
	s_mov_b32 s55, 0
	v_add_u32_e32 v212, 0xd000, v209
	v_add_u32_e32 v213, 0xd020, v209
	v_add_u32_e32 v214, 0xd040, v209
	v_add_u32_e32 v215, 0xd060, v209
	v_mov_b32_e32 v219, 0xf149f2ca
	v_mov_b32_e32 v217, 0
	v_add_u32_e32 v216, 0x3000, v211
	v_mov_b64_e32 v[28:29], v[12:13]
	v_mov_b64_e32 v[26:27], v[10:11]
	v_mov_b64_e32 v[24:25], v[8:9]
	v_mov_b64_e32 v[22:23], v[6:7]
	v_mov_b64_e32 v[20:21], v[4:5]
	v_mov_b64_e32 v[18:19], v[2:3]
	v_mov_b64_e32 v[16:17], v[0:1]
	v_mov_b64_e32 v[44:45], v[12:13]
	v_mov_b64_e32 v[42:43], v[10:11]
	v_mov_b64_e32 v[40:41], v[8:9]
	v_mov_b64_e32 v[38:39], v[6:7]
	v_mov_b64_e32 v[36:37], v[4:5]
	v_mov_b64_e32 v[34:35], v[2:3]
	v_mov_b64_e32 v[32:33], v[0:1]
	v_mov_b64_e32 v[60:61], v[12:13]
	v_mov_b64_e32 v[58:59], v[10:11]
	v_mov_b64_e32 v[56:57], v[8:9]
	v_mov_b64_e32 v[54:55], v[6:7]
	v_mov_b64_e32 v[52:53], v[4:5]
	v_mov_b64_e32 v[50:51], v[2:3]
	v_mov_b64_e32 v[48:49], v[0:1]
	s_branch .LBB0_332

; __device__ __forceinline__ void attn_item(const Params& p, unsigned char* smem, int b, int h, int qb, float lam) {
;     ...
;   auto gload = [&](u32x4 (&rk)[4], u32x4 (&rv)[4], int kt) {
; #pragma unroll
;     for (int i = 0; i < 4; ++i) {
;       rk[i] = *(const u32x4*)(kbase + (size_t)(kt * 64 + kr + 16 * i) * 1024 + kc * 8);
;       rv[i] = *(const u32x4*)(vbase + (size_t)(vr + 32 * i) * LPAD + kt * 64 + vc * 8);
;     }
;   };
;     ...
;     if (kt + 2 < ntiles) gload(ak, av, kt + 2);
.LBB0_332:
	s_add_i32 s56, s54, -3
	s_cmp_lt_u32 s56, s19
	s_cselect_b64 s[14:15], -1, 0
	s_cmp_ge_u32 s56, s19
	s_cselect_b64 s[16:17], -1, 0
	s_and_b64 vcc, exec, s[16:17]
	s_cbranch_vccnz .LBB0_334
	s_add_i32 s8, s55, 0x80
	s_lshl_b64 s[58:59], s[8:9], 11
	s_add_u32 s74, s84, s58
	s_addc_u32 s75, s85, s59
	s_lshl_b64 s[58:59], s[8:9], 1
	s_add_u32 s90, s86, s58
	s_addc_u32 s91, s87, s59
	global_load_dwordx4 v[100:103], v248, s[74:75]
	global_load_dwordx4 v[96:99], v252, s[90:91]
	global_load_dwordx4 v[104:107], v249, s[74:75]
	global_load_dwordx4 v[108:111], v253, s[90:91]
	global_load_dwordx4 v[132:135], v250, s[74:75]
	global_load_dwordx4 v[128:131], v254, s[90:91]
	global_load_dwordx4 v[136:139], v251, s[74:75]
	global_load_dwordx4 v[140:143], v255, s[90:91]

; __device__ __forceinline__ void attn_item(const Params& p, unsigned char* smem, int b, int h, int qb, float lam) {
;     ...
;   auto gload = [&](u32x4 (&rk)[4], u32x4 (&rv)[4], int kt) {
; #pragma unroll
;     for (int i = 0; i < 4; ++i) {
;       rk[i] = *(const u32x4*)(kbase + (size_t)(kt * 64 + kr + 16 * i) * 1024 + kc * 8);
;       rv[i] = *(const u32x4*)(vbase + (size_t)(vr + 32 * i) * LPAD + kt * 64 + vc * 8);
;     }
;   };
;     ...
;     float rsum = 0.f;
; #pragma unroll
;     for (int mt = 0; mt < 2; ++mt)
; #pragma unroll
;       for (int r = 0; r < 16; ++r) { float pv = __builtin_amdgcn_exp2f(st[mt][r] - m_new); st[mt][r] = pv; rsum += pv; }
;     l_run = l_run * alpha + rsum; m_run = m_new;
.LBB0_338:
	v_pk_add_f32 v[82:83], v[82:83], v[84:85]
	v_pk_add_f32 v[86:87], v[86:87], v[88:89]
	v_pk_add_f32 v[90:91], v[90:91], v[92:93]
	v_pk_add_f32 v[64:65], v[64:65], v[66:67]
	v_pk_add_f32 v[68:69], v[68:69], v[70:71]
	v_pk_add_f32 v[72:73], v[72:73], v[74:75]
	v_pk_add_f32 v[76:77], v[76:77], v[78:79]
	v_add_f32_e32 v81, v81, v219
	v_pk_add_f32 v[82:83], v[82:83], v[86:87]
	v_pk_add_f32 v[90:91], v[90:91], v[94:95]
	v_pk_add_f32 v[64:65], v[64:65], v[68:69]
	v_pk_add_f32 v[72:73], v[72:73], v[76:77]
	v_pk_add_f32 v[82:83], v[82:83], v[90:91]
	v_pk_add_f32 v[64:65], v[64:65], v[72:73]
	v_pk_add_f32 v[64:65], v[64:65], v[82:83]
	v_add_f32_e32 v64, v64, v65
	v_add_f32_e32 v64, v64, v81
	s_waitcnt lgkmcnt(0)
	s_barrier
	v_fma_f32 v221, v217, v80, v64
	s_andn2_b64 vcc, exec, s[16:17]
	s_cbranch_vccnz .LBB0_345
	s_cmp_ge_u32 s54, s53
	s_cbranch_scc1 .LBB0_341
	s_add_i32 s8, s55, 0xc0
	s_lshl_b64 s[16:17], s[8:9], 11
	s_add_u32 s74, s84, s16
	s_addc_u32 s75, s85, s17
	s_lshl_b64 s[16:17], s[8:9], 1
	s_add_u32 s90, s86, s16
	s_addc_u32 s91, s87, s17
	global_load_dwordx4 v[148:151], v248, s[74:75]
	global_load_dwordx4 v[144:147], v252, s[90:91]
	global_load_dwordx4 v[152:155], v249, s[74:75]
	global_load_dwordx4 v[156:159], v253, s[90:91]
	global_load_dwordx4 v[164:167], v250, s[74:75]
	global_load_dwordx4 v[160:163], v254, s[90:91]
	global_load_dwordx4 v[168:171], v251, s[74:75]
	global_load_dwordx4 v[172:175], v255, s[90:91]
